# prep items: static s_setprio 1 for waves 4-7 during the work-queue phase (reset before the phase barrier)
# speedup vs baseline: 1.0037x; 1.0037x over previous
; DI unsigned xb_add(unsigned* p, unsigned v) { return __hip_atomic_fetch_add(p, v, __ATOMIC_RELAXED, __HIP_MEMORY_SCOPE_AGENT); }
; #define ITEM_BEGIN { size_t z_ = 0; asm volatile("" : "+s"(z_)); q.ws = p.ws + z_; sm = smem + osgpr(0); }
; __global__ __launch_bounds__(512, 2) void mega(P p) {
;     ...
;             if (threadIdx.x == 0) qw[0] = xb_add(qctr, 1u);
;             __syncthreads();
;             int it = (int)qw[0];
;             __syncthreads();
;             while (it < ntot) {
;                 ITEM_BEGIN
;                 if (threadIdx.x == 0) nxt = xb_add(qctr, 1u);
.LBB0_241:
	s_or_b64 exec, exec, s[0:1]
	v_readlane_b32 s0, v254, 34
	s_waitcnt lgkmcnt(0)
	s_barrier
	v_mov_b32_e32 v0, s0
	ds_read_b32 v0, v0
	s_waitcnt lgkmcnt(0)
	s_barrier
	v_cmp_le_i32_e32 vcc, s88, v0
	v_readfirstlane_b32 s28, v0
	s_cbranch_vccnz .LBB0_333
.LBB0_242:
	v_readfirstlane_b32 s98, v166
	s_nop 0
	s_lshr_b32 s98, s98, 6
	s_cmp_ge_u32 s98, 4
	s_cbranch_scc0 .Lprep_prio_done
	s_setprio 1
.Lprep_prio_done:
	s_mov_b64 s[0:1], 0
	s_mov_b32 s45, s19
	s_mov_b64 s[36:37], exec
	v_readlane_b32 s2, v253, 1
	v_readlane_b32 s3, v253, 2
	s_and_b64 s[2:3], s[36:37], s[2:3]
	s_mov_b64 exec, s[2:3]
	s_cbranch_execz .LBB0_246
	s_mov_b64 s[40:41], exec
	v_mbcnt_lo_u32_b32 v0, s40, 0
	v_mbcnt_hi_u32_b32 v0, s41, v0
	v_cmp_eq_u32_e32 vcc, 0, v0
	s_and_saveexec_b64 s[38:39], vcc
	s_cbranch_execz .LBB0_245
	s_bcnt1_i32_b64 s2, s[40:41]
	v_mov_b32_e32 v1, s2
	v_readlane_b32 s2, v254, 60
	v_readlane_b32 s3, v254, 61
	s_nop 4
	global_atomic_add v111, v133, v1, s[2:3] sc0

; DI unsigned xb_add(unsigned* p, unsigned v) { return __hip_atomic_fetch_add(p, v, __ATOMIC_RELAXED, __HIP_MEMORY_SCOPE_AGENT); }
; DI void xcd_barrier(const XcdBarrier& b) {
;     asm volatile("s_waitcnt vmcnt(0)" ::: "memory");
;     __syncthreads();
;     if (threadIdx.x == 0) {
;         unsigned* bar = b.bar;
;         __builtin_amdgcn_s_waitcnt(0);
;         unsigned nloc = b.st[0], nx = b.st[1];
;         if (nloc == 0u) { xcd_barrier_complete(bar, b.x, nloc, nx); b.st[0] = nloc; b.st[1] = nx; }
;         const unsigned old = xb_add(&bar[XB_XSUB(b.x)], 1u);
.LBB0_333:
	s_setprio 0
	s_waitcnt vmcnt(0)
	s_barrier
	s_mov_b64 s[0:1], exec
	v_readlane_b32 s2, v253, 1
	v_readlane_b32 s12, v254, 56
	v_readlane_b32 s3, v253, 2
	v_readlane_b32 s13, v254, 57
	s_and_b64 s[2:3], s[0:1], s[2:3]
	v_readlane_b32 s13, v254, 62
	s_mov_b64 exec, s[2:3]
	s_cbranch_execz .LBB0_381
	v_readlane_b32 s2, v254, 32
	s_waitcnt vmcnt(0) expcnt(0) lgkmcnt(0)
	s_nop 0
	v_mov_b32_e32 v0, s2
	ds_read_b32 v2, v0
	v_readlane_b32 s2, v254, 33
	s_waitcnt lgkmcnt(0)
	v_cmp_ne_u32_e32 vcc, 0, v2
	v_mov_b32_e32 v0, s2
	ds_read_b32 v0, v0
	s_cbranch_vccnz .LBB0_349
	s_mov_b32 s2, 1
	s_branch .LBB0_337
